# attention k-loop softmax row-max: ds_bpermute xor16/xor32 replaced by v_permlane16_swap/v_permlane32_swap (same max, no LDS round trip)
# speedup vs baseline: 1.0048x; 1.0048x over previous
.LBB0_720:
	s_or_b64 exec, exec, s[10:11]
	s_and_b32 s13, 1, s12
	s_cselect_b32 s10, 0, 0x8c00
	s_add_i32 s10, s10, 16
	v_add3_u32 v114, s10, v158, v105
	ds_read_b128 v[118:121], v114
	ds_read_b128 v[122:125], v114 offset:64
	ds_read_b128 v[126:129], v114 offset:4352
	ds_read_b128 v[130:133], v114 offset:4416
	s_waitcnt lgkmcnt(3)
	v_mfma_f32_16x16x32_bf16 v[118:121], v[118:121], v[36:39], 0
	s_waitcnt lgkmcnt(1)
	v_mfma_f32_16x16x32_bf16 v[126:129], v[126:129], v[36:39], 0
	s_nop 0
	v_mfma_f32_16x16x32_bf16 v[118:121], v[122:125], v[40:43], v[118:121]
	ds_read_b128 v[122:125], v114 offset:8704
	s_waitcnt lgkmcnt(1)
	v_mfma_f32_16x16x32_bf16 v[126:129], v[130:133], v[40:43], v[126:129]
	ds_read_b128 v[130:133], v114 offset:8768
	ds_read_b128 v[138:141], v114 offset:13056
	ds_read_b128 v[160:163], v114 offset:13120
	s_waitcnt lgkmcnt(3)
	v_mfma_f32_16x16x32_bf16 v[122:125], v[122:125], v[36:39], 0
	s_waitcnt lgkmcnt(2)
	v_mfma_f32_16x16x32_bf16 v[130:133], v[130:133], v[40:43], v[122:125]
	s_nop 5
	v_max3_f32 v122, v118, s26, v119
	v_max3_f32 v122, v122, v120, v121
	v_max3_f32 v134, v122, v126, v127
	s_waitcnt lgkmcnt(1)
	v_mfma_f32_16x16x32_bf16 v[122:125], v[138:141], v[36:39], 0
	v_max3_f32 v134, v134, v128, v129
	v_max3_f32 v134, v134, v130, v131
	v_max3_f32 v134, v134, v132, v133
	s_waitcnt lgkmcnt(0)
	v_mfma_f32_16x16x32_bf16 v[138:141], v[160:163], v[40:43], v[122:125]
	s_nop 7
	v_max3_f32 v122, v134, v138, v139
	v_max3_f32 v122, v122, v140, v141
	v_mul_f32_e32 v134, 0x3e38aa3b, v122
	v_mul_f32_e32 v135, 0x3e38aa3b, v122
	ds_read_b128 v[122:125], v114 offset:128
	ds_read_b128 v[166:169], v114 offset:192
	ds_read_b128 v[170:173], v114 offset:4544
	s_nop 0
	v_permlane16_swap_b32_e32 v134, v135
	v_max_f32_e32 v134, v134, v135
	v_mov_b32_e32 v135, v134
	s_nop 1
	v_permlane32_swap_b32_e32 v134, v135
	s_waitcnt lgkmcnt(2)
	v_mfma_f32_16x16x32_bf16 v[122:125], v[122:125], v[48:51], 0
	v_max3_f32 v159, v117, v134, v135
	v_sub_f32_e32 v134, v117, v159
	v_fma_f32 v117, v118, s27, -v159
	v_fma_f32 v118, v119, s27, -v159
	v_fma_f32 v119, v120, s27, -v159
	v_fma_f32 v120, v121, s27, -v159
	v_exp_f32_e32 v162, v118
	v_exp_f32_e32 v163, v119
	v_exp_f32_e32 v164, v120
	ds_read_b128 v[118:121], v114 offset:4480
	s_waitcnt lgkmcnt(2)
	v_mfma_f32_16x16x32_bf16 v[174:177], v[166:169], v[52:55], v[122:125]
	v_exp_f32_e32 v161, v117
	v_fma_f32 v117, v126, s27, -v159
	v_exp_f32_e32 v165, v117
	ds_read_b128 v[122:125], v114 offset:8832
	s_waitcnt lgkmcnt(1)
	v_mfma_f32_16x16x32_bf16 v[118:121], v[118:121], v[48:51], 0
	v_fma_f32 v117, v127, s27, -v159
	v_exp_f32_e32 v166, v117
	v_fma_f32 v117, v128, s27, -v159
	v_fma_f32 v135, v129, s27, -v159
	ds_read_b128 v[126:129], v114 offset:8896
	v_mfma_f32_16x16x32_bf16 v[178:181], v[170:173], v[52:55], v[118:121]
	ds_read_b128 v[168:171], v114 offset:13184
	ds_read_b128 v[182:185], v114 offset:13248
	v_fma_f32 v114, v132, s27, -v159
	s_waitcnt lgkmcnt(3)
	v_mfma_f32_16x16x32_bf16 v[122:125], v[122:125], v[48:51], 0
	v_fma_f32 v118, v130, s27, -v159
	v_exp_f32_e32 v121, v118
	v_fma_f32 v118, v131, s27, -v159
	s_waitcnt lgkmcnt(2)
	v_mfma_f32_16x16x32_bf16 v[186:189], v[126:129], v[52:55], v[122:125]
	v_exp_f32_e32 v119, v135
	v_exp_f32_e32 v136, v134
	v_exp_f32_e32 v117, v117
	s_waitcnt lgkmcnt(1)
	v_mfma_f32_16x16x32_bf16 v[128:131], v[168:171], v[48:51], 0
	v_exp_f32_e32 v123, v118
	v_max3_f32 v118, v174, s26, v175
	v_max3_f32 v118, v118, v176, v177
	s_waitcnt lgkmcnt(0)
	v_mfma_f32_16x16x32_bf16 v[182:185], v[182:185], v[52:55], v[128:131]
	v_max3_f32 v118, v118, v178, v179
	v_max3_f32 v118, v118, v180, v181
	v_max3_f32 v118, v118, v186, v187
	v_max3_f32 v118, v118, v188, v189
	v_exp_f32_e32 v125, v114
	s_nop 2
	v_max3_f32 v118, v118, v182, v183
	v_max3_f32 v118, v118, v184, v185
	v_mul_f32_e32 v118, 0x3e38aa3b, v118
	v_fma_f32 v114, v133, s27, -v159
	v_mov_b32_e32 v120, v118
	v_exp_f32_e32 v127, v114
	v_fma_f32 v114, v138, s27, -v159
	v_permlane16_swap_b32_e32 v118, v120
	v_exp_f32_e32 v129, v114
	v_max_f32_e32 v118, v118, v120
	v_fma_f32 v114, v139, s27, -v159
	v_mov_b32_e32 v120, v118
	v_exp_f32_e32 v131, v114
	v_fma_f32 v114, v140, s27, -v159
	v_permlane32_swap_b32_e32 v118, v120
	v_exp_f32_e32 v133, v114
	v_fma_f32 v114, v141, s27, -v159
	v_max3_f32 v160, v116, v118, v120
	v_exp_f32_e32 v135, v114
	v_sub_f32_e32 v114, v116, v160
	v_fma_f32 v116, v174, s27, -v160
	v_exp_f32_e32 v167, v116
	v_fma_f32 v116, v175, s27, -v160
	v_exp_f32_e32 v168, v116
	v_fma_f32 v116, v176, s27, -v160
	v_exp_f32_e32 v169, v116
	v_fma_f32 v116, v177, s27, -v160
	v_exp_f32_e32 v138, v114
	v_lshlrev_b32_e32 v114, 1, v3
	v_exp_f32_e32 v170, v116
	v_fma_f32 v116, v178, s27, -v160
	v_add3_u32 v139, s10, v115, v114
	v_add3_u32 v178, s10, v152, v114
	v_add_u32_e32 v173, 0x4000, v139
	v_add_u32_e32 v190, 0x4000, v178
	v_fma_f32 v128, v182, s27, -v160
	v_fma_f32 v130, v183, s27, -v160
	v_fma_f32 v132, v184, s27, -v160
	v_fma_f32 v134, v185, s27, -v160
	ds_read2_b64 v[174:177], v173 offset0:128 offset1:132
	ds_read2_b64 v[182:185], v190 offset0:128 offset1:132
	v_exp_f32_e32 v171, v116
	v_fma_f32 v116, v179, s27, -v160
	v_exp_f32_e32 v172, v116
	v_fma_f32 v116, v180, s27, -v160
	v_fma_f32 v118, v181, s27, -v160
	v_exp_f32_e32 v116, v116
	v_exp_f32_e32 v118, v118
	v_pk_mul_f32 v[98:99], v[98:99], v[136:137] op_sel_hi:[1,0]
	v_pk_mul_f32 v[96:97], v[96:97], v[136:137] op_sel_hi:[1,0]
	v_pk_mul_f32 v[94:95], v[94:95], v[136:137] op_sel_hi:[1,0]
	v_pk_mul_f32 v[92:93], v[92:93], v[136:137] op_sel_hi:[1,0]
	v_cvt_pk_bf16_f32 v143, v117, v119
	v_cvt_pk_bf16_f32 v142, v165, v166
	v_cvt_pk_bf16_f32 v141, v163, v164
	v_cvt_pk_bf16_f32 v140, v161, v162
	v_pk_mul_f32 v[82:83], v[82:83], v[138:139] op_sel_hi:[1,0]
	v_pk_mul_f32 v[80:81], v[80:81], v[138:139] op_sel_hi:[1,0]
	v_cvt_pk_bf16_f32 v181, v116, v118
	v_cvt_pk_bf16_f32 v180, v171, v172
	v_cvt_pk_bf16_f32 v179, v169, v170
	v_cvt_pk_bf16_f32 v178, v167, v168
	v_pk_mul_f32 v[70:71], v[70:71], v[138:139] op_sel_hi:[1,0]
	v_pk_mul_f32 v[68:69], v[68:69], v[138:139] op_sel_hi:[1,0]
	s_waitcnt lgkmcnt(1)
	v_mfma_f32_16x16x32_bf16 v[96:99], v[174:177], v[140:143], v[96:99]
	v_mul_f32_e64 v78, v78, v136
	v_mul_f32_e64 v79, v79, v136
	v_pk_mul_f32 v[76:77], v[76:77], v[136:137] op_sel_hi:[1,0]
	v_pk_mul_f32 v[74:75], v[74:75], v[136:137] op_sel_hi:[1,0]
	v_mfma_f32_16x16x32_bf16 v[80:83], v[174:177], v[178:181], v[80:83]
	v_add3_u32 v174, s10, v153, v114
	v_add_u32_e32 v191, 0x4000, v174
	ds_read2_b64 v[174:177], v191 offset0:128 offset1:132
	s_waitcnt lgkmcnt(1)
	v_mfma_f32_16x16x32_bf16 v[92:95], v[182:185], v[140:143], v[92:95]
	v_mul_f32_e64 v58, v58, v138
	v_mul_f32_e64 v59, v59, v138
	v_pk_mul_f32 v[56:57], v[56:57], v[138:139] op_sel_hi:[1,0]
	v_pk_mul_f32 v[72:73], v[72:73], v[136:137] op_sel_hi:[1,0]
	v_mfma_f32_16x16x32_bf16 v[68:71], v[182:185], v[178:181], v[68:71]
	v_add3_u32 v182, s10, v154, v114
	v_add_u32_e32 v192, 0x4000, v182
	ds_read2_b64 v[182:185], v192 offset0:128 offset1:132
	v_add_u32_e32 v193, 0x6800, v139
	v_pk_mul_f32 v[26:27], v[26:27], v[138:139] op_sel_hi:[1,0]
	v_pk_mul_f32 v[24:25], v[24:25], v[138:139] op_sel_hi:[1,0]
	v_add_u32_e32 v194, 0x7000, v139
	s_waitcnt lgkmcnt(1)
	v_mfma_f32_16x16x32_bf16 v[76:79], v[174:177], v[140:143], v[76:79]
	v_mul_f32_e64 v62, v62, v136
	v_mul_f32_e64 v63, v63, v136
	v_pk_mul_f32 v[60:61], v[60:61], v[136:137] op_sel_hi:[1,0]
	v_pk_mul_f32 v[30:31], v[30:31], v[136:137] op_sel_hi:[1,0]
	v_mfma_f32_16x16x32_bf16 v[56:59], v[174:177], v[178:181], v[56:59]
	ds_read2_b64 v[174:177], v193 offset1:4
	v_pk_mul_f32 v[66:67], v[66:67], v[138:139] op_sel_hi:[1,0]
	v_pk_mul_f32 v[64:65], v[64:65], v[138:139] op_sel_hi:[1,0]
	s_waitcnt lgkmcnt(1)
	v_mfma_f32_16x16x32_bf16 v[72:75], v[182:185], v[140:143], v[72:75]
	v_mul_f32_e64 v28, v28, v136
	v_mul_f32_e64 v29, v29, v136
	v_add_u32_e32 v195, 0x7800, v139
	v_pk_mul_f32 v[46:47], v[46:47], v[138:139] op_sel_hi:[1,0]
	v_mfma_f32_16x16x32_bf16 v[24:27], v[182:185], v[178:181], v[24:27]
	ds_read2_b64 v[182:185], v194 offset0:32 offset1:36
	v_pk_mul_f32 v[44:45], v[44:45], v[138:139] op_sel_hi:[1,0]
	v_add_u32_e32 v139, 0x8000, v139
	s_waitcnt lgkmcnt(1)
	v_mfma_f32_16x16x32_bf16 v[60:63], v[174:177], v[140:143], v[60:63]
	v_mul_f32_e64 v34, v34, v138
	v_mul_f32_e64 v35, v35, v138
	v_pk_mul_f32 v[32:33], v[32:33], v[138:139] op_sel_hi:[1,0]
	v_pk_mul_f32 v[90:91], v[90:91], v[138:139] op_sel_hi:[1,0]
	v_mfma_f32_16x16x32_bf16 v[64:67], v[174:177], v[178:181], v[64:67]
	ds_read2_b64 v[174:177], v195 offset0:64 offset1:68
	v_pk_mul_f32 v[88:89], v[88:89], v[138:139] op_sel_hi:[1,0]
	v_fma_f32 v120, v186, s27, -v160
	s_waitcnt lgkmcnt(1)
	v_mfma_f32_16x16x32_bf16 v[28:31], v[182:185], v[140:143], v[28:31]
	v_fma_f32 v122, v187, s27, -v160
	v_fma_f32 v124, v188, s27, -v160
	v_fma_f32 v126, v189, s27, -v160
	v_mfma_f32_16x16x32_bf16 v[44:47], v[182:185], v[178:181], v[44:47]
	ds_read2_b64 v[182:185], v139 offset0:96 offset1:100
	v_exp_f32_e32 v120, v120
	v_exp_f32_e32 v122, v122
	s_waitcnt lgkmcnt(1)
	v_mfma_f32_16x16x32_bf16 v[32:35], v[174:177], v[178:181], v[32:35]
	v_exp_f32_e32 v124, v124
	v_exp_f32_e32 v126, v126
	v_exp_f32_e32 v128, v128
	s_waitcnt lgkmcnt(0)
	v_mfma_f32_16x16x32_bf16 v[88:91], v[182:185], v[178:181], v[88:91]
	ds_read2_b64 v[178:181], v190 offset0:136 offset1:140
	v_exp_f32_e32 v130, v130
	v_exp_f32_e32 v132, v132
	v_exp_f32_e32 v134, v134
	v_pk_mul_f32 v[22:23], v[22:23], v[136:137] op_sel_hi:[1,0]
	v_pk_mul_f32 v[20:21], v[20:21], v[136:137] op_sel_hi:[1,0]
	v_pk_mul_f32 v[86:87], v[86:87], v[136:137] op_sel_hi:[1,0]
	v_pk_mul_f32 v[84:85], v[84:85], v[136:137] op_sel_hi:[1,0]
	v_mfma_f32_16x16x32_bf16 v[20:23], v[174:177], v[140:143], v[20:23]
	v_cvt_pk_bf16_f32 v177, v133, v135
	v_cvt_pk_bf16_f32 v176, v129, v131
	v_cvt_pk_bf16_f32 v175, v125, v127
	v_mfma_f32_16x16x32_bf16 v[84:87], v[182:185], v[140:143], v[84:87]
	v_cvt_pk_bf16_f32 v174, v121, v123
	v_cvt_pk_bf16_f32 v143, v132, v134
	v_cvt_pk_bf16_f32 v142, v128, v130
	v_cvt_pk_bf16_f32 v141, v124, v126
	v_cvt_pk_bf16_f32 v140, v120, v122
	s_waitcnt lgkmcnt(0)
	v_mfma_f32_16x16x32_bf16 v[92:95], v[178:181], v[174:177], v[92:95]
	ds_read2_b64 v[186:189], v173 offset0:136 offset1:140
	v_mfma_f32_16x16x32_bf16 v[68:71], v[178:181], v[140:143], v[68:71]
	ds_read2_b64 v[178:181], v191 offset0:136 offset1:140
	s_waitcnt lgkmcnt(0)
	v_mfma_f32_16x16x32_bf16 v[76:79], v[178:181], v[174:177], v[76:79]
	v_mfma_f32_16x16x32_bf16 v[56:59], v[178:181], v[140:143], v[56:59]
	ds_read2_b64 v[178:181], v192 offset0:136 offset1:140
	s_waitcnt lgkmcnt(0)
	v_mfma_f32_16x16x32_bf16 v[72:75], v[178:181], v[174:177], v[72:75]
	v_mfma_f32_16x16x32_bf16 v[24:27], v[178:181], v[140:143], v[24:27]
	ds_read2_b64 v[178:181], v193 offset0:8 offset1:12
	s_waitcnt lgkmcnt(0)
	v_mfma_f32_16x16x32_bf16 v[60:63], v[178:181], v[174:177], v[60:63]
	v_mfma_f32_16x16x32_bf16 v[64:67], v[178:181], v[140:143], v[64:67]
	ds_read2_b64 v[178:181], v194 offset0:40 offset1:44
	s_waitcnt lgkmcnt(0)
	v_mfma_f32_16x16x32_bf16 v[28:31], v[178:181], v[174:177], v[28:31]
	v_mfma_f32_16x16x32_bf16 v[44:47], v[178:181], v[140:143], v[44:47]
	ds_read2_b64 v[178:181], v195 offset0:72 offset1:76
	s_waitcnt lgkmcnt(0)
	v_mfma_f32_16x16x32_bf16 v[20:23], v[178:181], v[174:177], v[20:23]
	v_mfma_f32_16x16x32_bf16 v[32:35], v[178:181], v[140:143], v[32:35]
	ds_read2_b64 v[178:181], v139 offset0:104 offset1:108
	v_mfma_f32_16x16x32_bf16 v[96:99], v[186:189], v[174:177], v[96:99]
	v_mfma_f32_16x16x32_bf16 v[80:83], v[186:189], v[140:143], v[80:83]
	s_waitcnt lgkmcnt(0)
	v_mfma_f32_16x16x32_bf16 v[84:87], v[178:181], v[174:177], v[84:87]
	v_mfma_f32_16x16x32_bf16 v[88:91], v[178:181], v[140:143], v[88:91]
	s_and_saveexec_b64 s[10:11], s[6:7]
	s_cbranch_execz .LBB0_717
	s_cmp_eq_u32 s13, 1
	s_cselect_b32 s6, 0x8c00, 0
	s_add_i32 s6, s6, 16
	v_add3_u32 v139, s6, v155, v102
	s_waitcnt vmcnt(0)
	ds_write_b128 v139, v[4:7]
	ds_write_b128 v139, v[8:11] offset:8704
	v_add3_u32 v139, s6, v156, v104
	ds_write_b128 v139, v[12:15] offset:17408
	ds_write_b128 v139, v[16:19] offset:26624
	s_branch .LBB0_717
